# v40 + XCD barrier leader posts the XGEN release atomic before issuing its own agent-scope L1 invalidate (waiters still acquire after observing the release)
# baseline (speedup 1.0000x reference)
; __device__ __forceinline__ unsigned xb_add(unsigned* p, unsigned v) { return __hip_atomic_fetch_add(p, v, __ATOMIC_RELAXED, __HIP_MEMORY_SCOPE_AGENT); }
; __device__ __forceinline__ void xcd_barrier(unsigned* bar, volatile LAS unsigned* st) {
;     ...
;             __builtin_amdgcn_fence(__ATOMIC_ACQUIRE, "agent");
;             xb_add(&bar[XB_XGEN(x)], 1u);
;             asm volatile("s_waitcnt vmcnt(0)" ::: "memory");
.LBB0_529:
	s_or_b64 exec, exec, s[6:7]
	s_mov_b64 s[6:7], exec
	v_mbcnt_lo_u32_b32 v0, s6, 0
	v_mbcnt_hi_u32_b32 v0, s7, v0
	v_cmp_eq_u32_e32 vcc, 0, v0
	s_waitcnt vmcnt(0)
	s_and_saveexec_b64 s[8:9], vcc
	s_cbranch_execz .LBB0_531
	s_bcnt1_i32_b64 s6, s[6:7]
	v_mov_b32_e32 v0, s6
	global_atomic_add v235, v0, s[4:5] offset:1024
.LBB0_531:
	s_or_b64 exec, exec, s[8:9]
	buffer_inv sc1
	s_waitcnt vmcnt(0)
